# selection: block ranks for the 4 query pairs of a wave computed in one loop with 4 LDS reads in flight; direct ballots
# speedup vs baseline: 1.0162x; 1.0030x over previous
; DEV void attn_item(LAS unsigned char* lds, const bf16_t* P, const bf16_t* QB, const bf16_t* KV, const bf16_t* KC, const bf16_t* VC, const float* rel_bias, bf16_t* OB, int b, int g, int qt) {
;     ...
;         for (int it = 0; it < 4; ++it) { const int q = wave * 8 + it * 2 + (lane >> 5), j = lane & 31;
;             const float v = IMPF[q * 32 + j]; int rank = 0;
;             for (int jp = 1; jp <= cur - 2; ++jp) { const float vp = IMPF[q * 32 + jp]; rank += (vp > v || (vp == v && jp < j)) ? 1 : 0; }
;             const bool sel = (j >= 1) && (j <= cur - 2) && (rank < need);
;             const unsigned long long bal = __ballot(sel);
;             const unsigned mq = forced | (unsigned)(lane < 32 ? bal : (bal >> 32));
;             if (j == 0) MASK[q] = mq; }
.LBB0_219:
	s_or_b64 exec, exec, s[4:5]
	s_sub_i32 s64, 30, s17
	v_lshrrev_b32_e32 v63, 5, v152
	s_sub_i32 s36, 29, s17
	v_lshl_or_b32 v66, v146, 3, v63
	s_cmp_gt_u32 s15, 2
	ds_write_b32 v62, v7 offset:6144
	s_cselect_b64 s[6:7], -1, 0
	s_cmp_lt_u32 s15, 3
	v_lshlrev_b32_e32 v64, 7, v66
	v_mov_b32_e32 v7, 0
	v_lshlrev_b32_e32 v65, 2, v60
	s_waitcnt lgkmcnt(0)
	s_barrier
	s_cbranch_scc1 .Lrk_none
	s_mov_b32 s4, 0x11d00
	v_add3_u32 v61, s4, v64, v65
	ds_read_b32 v70, v61
	ds_read_b32 v71, v61 offset:256
	ds_read_b32 v72, v61 offset:512
	ds_read_b32 v73, v61 offset:768
	v_add_u32_e32 v62, s4, v64
	v_mov_b32_e32 v74, 0
	v_mov_b32_e32 v75, 0
	v_mov_b32_e32 v76, 0
	v_mov_b32_e32 v77, 0
	s_mov_b32 s5, 1
.Lrk_loop:
	ds_read_b32 v78, v62 offset:4
	ds_read_b32 v79, v62 offset:260
	ds_read_b32 v80, v62 offset:516
	ds_read_b32 v81, v62 offset:772
	v_cmp_lt_u32_e64 s[42:43], s5, v60
	v_add_u32_e32 v62, 4, v62
	s_waitcnt lgkmcnt(0)
	v_cmp_gt_f32_e64 s[44:45], v78, v70
	v_cmp_eq_f32_e64 s[46:47], v78, v70
	v_cmp_gt_f32_e64 s[48:49], v79, v71
	v_cmp_eq_f32_e64 s[50:51], v79, v71
	v_cmp_gt_f32_e64 s[52:53], v80, v72
	v_cmp_eq_f32_e64 s[54:55], v80, v72
	v_cmp_gt_f32_e64 s[92:93], v81, v73
	v_cmp_eq_f32_e64 s[94:95], v81, v73
	s_and_b64 s[46:47], s[46:47], s[42:43]
	s_and_b64 s[50:51], s[50:51], s[42:43]
	s_and_b64 s[54:55], s[54:55], s[42:43]
	s_and_b64 s[94:95], s[94:95], s[42:43]
	s_or_b64 s[44:45], s[44:45], s[46:47]
	s_or_b64 s[48:49], s[48:49], s[50:51]
	s_or_b64 s[52:53], s[52:53], s[54:55]
	s_or_b64 s[92:93], s[92:93], s[94:95]
	s_add_i32 s5, s5, 1
	v_addc_co_u32_e64 v74, s[44:45], 0, v74, s[44:45]
	v_addc_co_u32_e64 v75, s[48:49], 0, v75, s[48:49]
	v_addc_co_u32_e64 v76, s[52:53], 0, v76, s[52:53]
	v_addc_co_u32_e64 v77, s[92:93], 0, v77, s[92:93]
	s_cmp_le_u32 s5, s36
	s_cbranch_scc1 .Lrk_loop
	s_branch .Lrk_done
.Lrk_none:
	v_mov_b32_e32 v74, 0
	v_mov_b32_e32 v75, 0
	v_mov_b32_e32 v76, 0
	v_mov_b32_e32 v77, 0
; #define LAS __attribute__((address_space(3)))
; DEV void attn_item(LAS unsigned char* lds, const bf16_t* P, const bf16_t* QB, const bf16_t* KV, const bf16_t* KC, const bf16_t* VC, const float* rel_bias, bf16_t* OB, int b, int g, int qt) {
;     ...
;         const int cur = qt;
;         const unsigned forced = 1u | (1u << cur) | (cur > 0 ? (1u << (cur - 1)) : 0u);
;         const int need = 8 - __popc(forced);
;         for (int it = 0; it < 4; ++it) { const int q = wave * 8 + it * 2 + (lane >> 5), j = lane & 31;
;             const float v = IMPF[q * 32 + j]; int rank = 0;
;             for (int jp = 1; jp <= cur - 2; ++jp) { const float vp = IMPF[q * 32 + jp]; rank += (vp > v || (vp == v && jp < j)) ? 1 : 0; }
;             const bool sel = (j >= 1) && (j <= cur - 2) && (rank < need);
;             const unsigned long long bal = __ballot(sel);
;             const unsigned mq = forced | (unsigned)(lane < 32 ? bal : (bal >> 32));
;             if (j == 0) MASK[q] = mq; }
;     }
;     __syncthreads();
;     const unsigned mymask = MASK[qs * 16 + fr];
;     unsigned anym = MASK[lane];
; #pragma unroll
;     for (int o = 32; o >= 1; o >>= 1) anym |= __shfl_xor(anym, o);
;     anym = __builtin_amdgcn_readfirstlane(anym);
;     {
;         float cbias[2]; cbias[0] = *(const LAS float*)(lds + btb + 512); cbias[1] = *(const LAS float*)(lds + btb + 512 + 516);
;         float mrun[2] = {NEG_, NEG_}, lrun[2] = {0.f, 0.f}; f32x4 O[2][4];
; #pragma unroll
;         for (int hh = 0; hh < 2; ++hh)
; #pragma unroll
;             for (int dt = 0; dt < 4; ++dt) O[hh][dt] = (f32x4){0.f, 0.f, 0.f, 0.f};
;         unsigned rem = anym & (qt >= 31 ? 0xffffffffu : ((2u << qt) - 1u)); rem &= ~1u;
;         int mode = 1, j = 0, buf = 0;
;         for (;;) {
;             kv_store(lds, pre, buf, tid);
.Lrk_done:
	s_lshr_b32 s4, 0x80000000, s17
	s_lshl_b32 s5, 1, s64
	s_cmp_lg_u32 s17, 31
	s_cselect_b32 s5, s5, 0
	s_or_b32 s4, s4, s5
	s_or_b32 s92, s4, 1
	s_bcnt1_i32_b32 s4, s92
	s_sub_i32 s93, 8, s4
	v_cmp_ne_u32_e32 vcc, 0, v60
	v_cmp_ge_i32_e64 s[44:45], s36, v60
	v_and_b32_e32 v67, 32, v150
	v_lshl_add_u32 v68, v66, 2, 0
	s_and_b64 s[4:5], vcc, s[44:45]
	v_add_u32_e32 v68, 0x11c00, v68
	v_cmp_eq_u32_e64 s[42:43], 0, v60
	v_cmp_gt_i32_e32 vcc, s93, v74
	s_and_b64 vcc, s[4:5], vcc
	s_nop 0
	v_lshrrev_b64 v[78:79], v67, vcc
	v_or_b32_e32 v78, s92, v78
	v_cmp_gt_i32_e32 vcc, s93, v75
	s_and_b64 vcc, s[4:5], vcc
	s_nop 0
	v_lshrrev_b64 v[80:81], v67, vcc
	v_or_b32_e32 v80, s92, v80
	v_cmp_gt_i32_e32 vcc, s93, v76
	s_and_b64 vcc, s[4:5], vcc
	s_nop 0
	v_lshrrev_b64 v[82:83], v67, vcc
	v_or_b32_e32 v82, s92, v82
	v_cmp_gt_i32_e32 vcc, s93, v77
	s_and_b64 vcc, s[4:5], vcc
	s_nop 0
	v_lshrrev_b64 v[84:85], v67, vcc
	v_or_b32_e32 v84, s92, v84
	s_and_saveexec_b64 s[4:5], s[42:43]
	ds_write_b32 v68, v78
	ds_write_b32 v68, v80 offset:8
	ds_write_b32 v68, v82 offset:16
	ds_write_b32 v68, v84 offset:24
	s_or_b64 exec, exec, s[4:5]
	s_add_i32 s4, 0, 0x11c00
	v_lshl_add_u32 v7, v152, 2, s4
	s_waitcnt lgkmcnt(0)
	s_barrier
	ds_read_b32 v7, v7
	v_lshlrev_b32_e32 v60, 2, v137
	v_lshlrev_b32_e32 v61, 2, v136
	v_add3_u32 v60, s4, v60, v61
	ds_read_b32 v127, v60
	s_waitcnt lgkmcnt(1)
	ds_bpermute_b32 v61, v144, v7
	v_and_b32_e32 v60, 0xffff0000, v149
	v_lshlrev_b32_e32 v126, 16, v149
	s_lshl_b32 s5, 2, s15
	s_waitcnt lgkmcnt(1)
	v_pk_fma_f32 v[134:135], v[126:127], v[2:3], 0 op_sel_hi:[0,1,0]
	s_waitcnt lgkmcnt(0)
	v_or_b32_e32 v7, v61, v7
	v_pk_fma_f32 v[116:117], v[60:61], v[44:45], 0 op_sel_hi:[0,1,0]
	ds_bpermute_b32 v44, v143, v7
	v_xor_b32_e32 v3, 4, v213
	v_pk_fma_f32 v[130:131], v[126:127], v[4:5], 0 op_sel_hi:[0,1,0]
	v_pk_fma_f32 v[132:133], v[126:127], v[32:33], 0 op_sel_hi:[0,1,0]
	s_add_i32 s5, s5, -1
	s_waitcnt lgkmcnt(0)
	v_or_b32_e32 v7, v44, v7
	v_xor_b32_e32 v44, 8, v213
	v_cmp_lt_i32_e32 vcc, v44, v153
	s_and_b32 s5, s5, -2
	s_cmp_lt_u32 s15, 31
	v_cndmask_b32_e32 v44, v213, v44, vcc
	v_lshlrev_b32_e32 v44, 2, v44
	ds_bpermute_b32 v44, v44, v7
	v_cmp_lt_i32_e32 vcc, v3, v153
	s_cselect_b32 s5, s5, -2
	v_pk_fma_f32 v[114:115], v[60:61], v[46:47], 0 op_sel_hi:[0,1,0]
	v_cndmask_b32_e32 v3, v213, v3, vcc
	s_waitcnt lgkmcnt(0)
	v_or_b32_e32 v2, v44, v7
	v_lshlrev_b32_e32 v3, 2, v3
	ds_bpermute_b32 v3, v3, v2
	v_pk_fma_f32 v[110:111], v[60:61], v[50:51], 0 op_sel_hi:[0,1,0]
	v_pk_fma_f32 v[112:113], v[60:61], v[48:49], 0 op_sel_hi:[0,1,0]
	v_pk_fma_f32 v[104:105], v[60:61], v[54:55], 0 op_sel_hi:[0,1,0]
	v_pk_fma_f32 v[108:109], v[60:61], v[52:53], 0 op_sel_hi:[0,1,0]
	s_waitcnt lgkmcnt(0)
	v_or_b32_e32 v4, v3, v2
	v_xor_b32_e32 v2, 2, v213
	v_cmp_lt_i32_e32 vcc, v2, v153
	v_and_b32_e32 v3, 0xffff0000, v148
	v_pk_fma_f32 v[102:103], v[60:61], v[58:59], 0 op_sel_hi:[0,1,0]
	v_cndmask_b32_e32 v2, v213, v2, vcc
	v_lshlrev_b32_e32 v2, 2, v2
	ds_bpermute_b32 v5, v2, v4
	v_lshlrev_b32_e32 v2, 16, v148
	v_mov_b32_e32 v148, 0
	v_pk_fma_f32 v[106:107], v[60:61], v[56:57], 0 op_sel_hi:[0,1,0]
	v_pk_fma_f32 v[128:129], v[126:127], v[34:35], 0 op_sel_hi:[0,1,0]
	s_waitcnt lgkmcnt(0)
	v_or_b32_e32 v32, v5, v4
	v_xor_b32_e32 v4, 1, v213
	v_cmp_lt_i32_e32 vcc, v4, v153
	v_pk_fma_f32 v[120:121], v[126:127], v[38:39], 0 op_sel_hi:[0,1,0]
	v_pk_fma_f32 v[124:125], v[126:127], v[36:37], 0 op_sel_hi:[0,1,0]
	v_cndmask_b32_e32 v4, v213, v4, vcc
	v_lshlrev_b32_e32 v4, 2, v4
	ds_bpermute_b32 v33, v4, v32
	v_pk_fma_f32 v[118:119], v[126:127], v[42:43], 0 op_sel_hi:[0,1,0]
	v_pk_fma_f32 v[122:123], v[126:127], v[40:41], 0 op_sel_hi:[0,1,0]
	v_and_b32_e32 v5, 0xffff0000, v147
	v_lshlrev_b32_e32 v4, 16, v147
	s_waitcnt lgkmcnt(0)
	v_or_b32_e32 v32, v33, v32
	v_add_u32_e32 v33, 0x200, v142
	ds_read2_b32 v[136:137], v33 offset1:129
	v_readfirstlane_b32 s4, v32
	v_mul_lo_u32 v32, v100, s24
	v_or_b32_e32 v32, v32, v152
	v_lshl_add_u32 v146, v32, 1, v221
	v_sub_u32_e64 v32, s15, 8 clamp
	v_mov_b32_e32 v7, v60
	s_mov_b32 s97, 1
	s_and_b32 s95, s4, s5
	v_readfirstlane_b32 s94, v32
	s_sub_i32 s17, 23, s17
	v_add_u32_e32 v145, 0, v145
	s_mov_b32 s50, 0
	v_mov_b32_e32 v150, 0xf149f2ca
	v_mov_b32_e32 v147, 0
	v_mov_b32_e32 v149, 0xf149f2ca
	v_mov_b32_e32 v151, 0
	v_mov_b32_e32 v48, 0
	v_mov_b32_e32 v49, v148
	v_mov_b32_e32 v50, v148
	v_mov_b32_e32 v51, v148
	v_mov_b32_e32 v36, 0
	v_mov_b32_e32 v37, v148
	v_mov_b32_e32 v38, v148
	v_mov_b32_e32 v39, v148
	v_mov_b32_e32 v40, 0
	v_mov_b32_e32 v41, v148
	v_mov_b32_e32 v42, v148
	v_mov_b32_e32 v43, v148
	v_mov_b32_e32 v32, 0
	v_mov_b32_e32 v33, v148
	v_mov_b32_e32 v34, v148
	v_mov_b32_e32 v35, v148
	v_mov_b32_e32 v60, 0
	v_mov_b32_e32 v61, v148
	v_mov_b32_e32 v62, v148
	v_mov_b32_e32 v63, v148
	v_mov_b32_e32 v52, 0
	v_mov_b32_e32 v53, v148
	v_mov_b32_e32 v54, v148
	v_mov_b32_e32 v55, v148
	v_mov_b32_e32 v56, 0
	v_mov_b32_e32 v57, v148
	v_mov_b32_e32 v58, v148
	v_mov_b32_e32 v59, v148
	v_mov_b32_e32 v44, 0
	v_mov_b32_e32 v45, v148
	v_mov_b32_e32 v46, v148
	v_mov_b32_e32 v47, v148
	v_readfirstlane_b32 s100, v210
	s_mov_b32 s98, 0
	s_waitcnt vmcnt(1)
	ds_write_b128 v139, v[24:27]
	s_waitcnt vmcnt(0)
	ds_write_b16 v146, v28
	ds_write_b16_d16_hi v146, v28 offset:144
	ds_write_b16 v146, v29 offset:288
	ds_write_b16_d16_hi v146, v29 offset:432
	ds_write_b16 v146, v30 offset:576
	ds_write_b16_d16_hi v146, v30 offset:720
	ds_write_b16 v146, v31 offset:864
	ds_write_b16_d16_hi v146, v31 offset:1008
	s_lshr_b32 s100, s100, 8
	s_mul_i32 s100, s100, 3
	s_waitcnt lgkmcnt(0)
	s_barrier
